# NSA window-branch first two K/V tiles prefetched during top-k into free VGPRs
# baseline (speedup 1.0000x reference)
; DI void kv_load(int tid, const bf16* Kb, const bf16* Vb, size_t stride, int row0, s16x8& kr, s16x8& vr) {
;   int row = tid >> 3, ch = (tid & 7) * 8;
;   kr = *(const s16x8*)(Kb + (size_t)(row0 + row) * stride + ch);
;   if (Vb) vr = *(const s16x8*)(Vb + (size_t)(row0 + row) * stride + ch);
; }
; __device__ void nsa_item(const Params& p, int item, char* smem) {
;     ...
;   {
;     const int tk = lane >> 3, sub = lane & 7;
;     const int tq2 = w * 8 + tk, t2 = t0 + tq2, cur = t2 >> 6;
;     unsigned long long key[16];
; #pragma unroll
;     for (int e = 0; e < 16; ++e) {
;       int j = sub * 16 + e;
;       float v = imp[tq2 * IMPW + j] + impe[tq2 * IMPW + j];
;       bool forced = (j == 0) || (j == cur) || (j == cur - 1);
;       if (forced) v += 1e4f;
;       bool vis = (64 * j <= t2);
;       unsigned hi = vis ? (__float_as_uint(v) + 1u) : 0u;
;       key[e] = ((unsigned long long)hi << 32) | (unsigned)(128 - j);
;     }
.LBB0_580:
	s_waitcnt vmcnt(0)
	v_mov_b32_e32 v224, s22
	v_and_b32_e32 v224, 0x1fc0, v224
	v_add_u32_e32 v224, v224, v14
	v_mov_b32_e32 v225, 0
	v_lshlrev_b64 v[224:225], 7, v[224:225]
	v_lshl_add_u64 v[224:225], s[40:41], 0, v[224:225]
	v_lshl_add_u64 v[224:225], v[224:225], 0, v[0:1]
	s_mov_b64 s[4:5], 0x1000000
	v_lshl_add_u64 v[226:227], v[224:225], 0, s[4:5]
	global_load_dwordx4 v[232:235], v[226:227], off
	s_mov_b64 s[4:5], 0x1200000
	v_lshl_add_u64 v[226:227], v[224:225], 0, s[4:5]
	global_load_dwordx4 v[236:239], v[226:227], off
	s_mov_b64 s[4:5], 0x1002000
	v_lshl_add_u64 v[226:227], v[224:225], 0, s[4:5]
	global_load_dwordx4 v[240:243], v[226:227], off
	s_mov_b64 s[4:5], 0x1202000
	v_lshl_add_u64 v[226:227], v[224:225], 0, s[4:5]
	global_load_dwordx4 v[244:247], v[226:227], off
	v_lshrrev_b32_e32 v2, 3, v82
	v_or_b32_e32 v3, v189, v2
	s_movk_i32 s0, 0x84
	v_lshlrev_b32_e32 v15, 4, v128
	v_mul_lo_u32 v68, v3, s0
	v_add_lshl_u32 v6, v68, v15, 2
	v_readlane_b32 s2, v255, 18
	v_add_u32_e32 v7, 0, v6
	s_waitcnt lgkmcnt(0)
	v_add_u32_e32 v6, s2, v6
	s_barrier
	ds_read_b64 v[8:9], v7 offset:36864
	ds_read_b64 v[10:11], v6
	v_add_u32_e32 v2, s20, v3
	v_ashrrev_i32_e32 v4, 6, v2
	v_add_u32_e32 v5, -1, v4
	v_cmp_eq_u32_e32 vcc, 0, v128
	v_cmp_eq_u32_e64 s[4:5], v15, v4
	s_waitcnt lgkmcnt(0)
	v_add_f32_e32 v6, v8, v10
	s_or_b64 s[0:1], vcc, s[4:5]
	v_cmp_eq_u32_e64 s[4:5], v15, v5
	s_or_b64 s[4:5], s[0:1], s[4:5]
	v_add_f32_e32 v7, 0x461c4000, v6
	v_cndmask_b32_e64 v6, v6, v7, s[4:5]
	v_lshlrev_b32_e32 v7, 10, v128
	v_add_u32_e32 v6, 1, v6
	v_cmp_le_i32_e64 s[4:5], v7, v2
	v_or_b32_e32 v8, 1, v15
	v_add_f32_e32 v9, v9, v11
	v_cndmask_b32_e64 v7, 0, v6, s[4:5]
	v_cmp_eq_u32_e64 s[4:5], v8, v4
	v_cmp_eq_u32_e64 s[6:7], v8, v5
	s_or_b64 s[4:5], s[4:5], s[6:7]
	v_add_f32_e32 v10, 0x461c4000, v9
	v_cndmask_b32_e64 v9, v9, v10, s[4:5]
	v_lshlrev_b32_e32 v10, 6, v8
	v_or_b32_e32 v49, 2, v15
	v_cmp_le_i32_e64 s[4:5], v10, v2
	v_add_lshl_u32 v10, v68, v49, 2
	v_add_u32_e32 v11, 0, v10
	v_add_u32_e32 v12, s2, v10
	ds_read_b64 v[10:11], v11 offset:36864
	ds_read_b64 v[12:13], v12
	v_add_u32_e32 v9, 1, v9
	v_or_b32_e32 v48, 3, v15
	v_cndmask_b32_e64 v9, 0, v9, s[4:5]
	v_cmp_eq_u32_e64 s[4:5], v48, v4
	s_waitcnt lgkmcnt(0)
	v_pk_add_f32 v[10:11], v[10:11], v[12:13]
	v_cmp_eq_u32_e64 s[8:9], v48, v5
	s_mov_b32 s0, 0x461c4000
	v_cmp_eq_u32_e64 s[6:7], v49, v4
	v_cmp_eq_u32_e64 s[36:37], v49, v5
	s_or_b64 s[4:5], s[4:5], s[8:9]
	v_pk_add_f32 v[12:13], v[10:11], s[0:1] op_sel_hi:[1,0]
	s_or_b64 s[6:7], s[6:7], s[36:37]
	v_cndmask_b32_e64 v11, v11, v13, s[4:5]
	v_lshlrev_b32_e32 v13, 6, v48
	v_cndmask_b32_e64 v10, v10, v12, s[6:7]
	v_lshlrev_b32_e32 v12, 6, v49
	v_add_u32_e32 v11, 1, v11
	v_cmp_le_i32_e64 s[4:5], v13, v2
	v_add_u32_e32 v10, 1, v10
	v_or_b32_e32 v53, 4, v15
	v_cndmask_b32_e64 v11, 0, v11, s[4:5]
	v_cmp_le_i32_e64 s[4:5], v12, v2
	v_sub_u32_e32 v12, 0x80, v49
	v_or_b32_e32 v52, 5, v15
	v_cndmask_b32_e64 v13, 0, v10, s[4:5]
	v_sub_u32_e32 v10, 0x80, v48
	v_add_lshl_u32 v48, v68, v53, 2
	v_add_u32_e32 v49, 0, v48
	v_add_u32_e32 v50, s2, v48
	ds_read_b64 v[48:49], v49 offset:36864
	ds_read_b64 v[50:51], v50
	v_cmp_eq_u32_e64 s[4:5], v52, v4
	v_cmp_eq_u32_e64 s[8:9], v52, v5
	v_cmp_eq_u32_e64 s[6:7], v53, v4
	v_cmp_eq_u32_e64 s[36:37], v53, v5
	s_waitcnt lgkmcnt(0)
	v_pk_add_f32 v[48:49], v[48:49], v[50:51]
	s_or_b64 s[4:5], s[4:5], s[8:9]
	v_pk_add_f32 v[50:51], v[48:49], s[0:1] op_sel_hi:[1,0]
	s_or_b64 s[6:7], s[6:7], s[36:37]
	v_cndmask_b32_e64 v49, v49, v51, s[4:5]
	v_lshlrev_b32_e32 v51, 6, v52
	v_cndmask_b32_e64 v48, v48, v50, s[6:7]
	v_lshlrev_b32_e32 v50, 6, v53
	v_add_u32_e32 v49, 1, v49
	v_cmp_le_i32_e64 s[4:5], v51, v2
	v_add_u32_e32 v48, 1, v48
	v_or_b32_e32 v57, 6, v15
	v_cndmask_b32_e64 v49, 0, v49, s[4:5]
	v_cmp_le_i32_e64 s[4:5], v50, v2
	v_sub_u32_e32 v50, 0x80, v53
	v_or_b32_e32 v56, 7, v15
	v_cndmask_b32_e64 v51, 0, v48, s[4:5]
	v_sub_u32_e32 v48, 0x80, v52
	v_add_lshl_u32 v52, v68, v57, 2
	v_add_u32_e32 v53, 0, v52
	v_add_u32_e32 v54, s2, v52
	ds_read_b64 v[52:53], v53 offset:36864
	ds_read_b64 v[54:55], v54
	v_cmp_eq_u32_e64 s[4:5], v56, v4
	v_cmp_eq_u32_e64 s[8:9], v56, v5
	v_cmp_eq_u32_e64 s[6:7], v57, v4
	v_cmp_eq_u32_e64 s[36:37], v57, v5
	s_waitcnt lgkmcnt(0)
; __device__ void nsa_item(const Params& p, int item, char* smem) {
;     ...
;     for (int e = 0; e < 16; ++e) {
;       int j = sub * 16 + e;
;       float v = imp[tq2 * IMPW + j] + impe[tq2 * IMPW + j];
;       bool forced = (j == 0) || (j == cur) || (j == cur - 1);
;       if (forced) v += 1e4f;
;       bool vis = (64 * j <= t2);
;       unsigned hi = vis ? (__float_as_uint(v) + 1u) : 0u;
;       key[e] = ((unsigned long long)hi << 32) | (unsigned)(128 - j);
;     }
	v_pk_add_f32 v[52:53], v[52:53], v[54:55]
	s_or_b64 s[4:5], s[4:5], s[8:9]
	v_pk_add_f32 v[54:55], v[52:53], s[0:1] op_sel_hi:[1,0]
	s_or_b64 s[6:7], s[6:7], s[36:37]
	v_cndmask_b32_e64 v53, v53, v55, s[4:5]
	v_lshlrev_b32_e32 v55, 6, v56
	v_cndmask_b32_e64 v52, v52, v54, s[6:7]
	v_lshlrev_b32_e32 v54, 6, v57
	v_add_u32_e32 v53, 1, v53
	v_cmp_le_i32_e64 s[4:5], v55, v2
	v_add_u32_e32 v52, 1, v52
	v_or_b32_e32 v61, 8, v15
	v_cndmask_b32_e64 v53, 0, v53, s[4:5]
	v_cmp_le_i32_e64 s[4:5], v54, v2
	v_sub_u32_e32 v54, 0x80, v57
	v_or_b32_e32 v60, 9, v15
	v_cndmask_b32_e64 v55, 0, v52, s[4:5]
	v_sub_u32_e32 v52, 0x80, v56
	v_add_lshl_u32 v56, v68, v61, 2
	v_add_u32_e32 v57, 0, v56
	v_add_u32_e32 v58, s2, v56
	ds_read_b64 v[56:57], v57 offset:36864
	ds_read_b64 v[58:59], v58
	v_cmp_eq_u32_e64 s[4:5], v60, v4
	v_cmp_eq_u32_e64 s[8:9], v60, v5
	v_cmp_eq_u32_e64 s[6:7], v61, v4
	v_cmp_eq_u32_e64 s[36:37], v61, v5
	s_waitcnt lgkmcnt(0)
	v_pk_add_f32 v[56:57], v[56:57], v[58:59]
	s_or_b64 s[4:5], s[4:5], s[8:9]
	v_pk_add_f32 v[58:59], v[56:57], s[0:1] op_sel_hi:[1,0]
	s_or_b64 s[6:7], s[6:7], s[36:37]
	v_cndmask_b32_e64 v57, v57, v59, s[4:5]
	v_lshlrev_b32_e32 v59, 6, v60
	v_cndmask_b32_e64 v56, v56, v58, s[6:7]
	v_lshlrev_b32_e32 v58, 6, v61
	v_add_u32_e32 v57, 1, v57
	v_cmp_le_i32_e64 s[4:5], v59, v2
	v_add_u32_e32 v56, 1, v56
	v_or_b32_e32 v65, 10, v15
	v_cndmask_b32_e64 v57, 0, v57, s[4:5]
	v_cmp_le_i32_e64 s[4:5], v58, v2
	v_sub_u32_e32 v58, 0x80, v61
	v_or_b32_e32 v64, 11, v15
	v_cndmask_b32_e64 v59, 0, v56, s[4:5]
	v_sub_u32_e32 v56, 0x80, v60
	v_add_lshl_u32 v60, v68, v65, 2
	v_add_u32_e32 v61, 0, v60
	v_add_u32_e32 v62, s2, v60
	ds_read_b64 v[60:61], v61 offset:36864
	ds_read_b64 v[62:63], v62
	v_cmp_eq_u32_e64 s[4:5], v64, v4
	v_cmp_eq_u32_e64 s[8:9], v64, v5
	v_cmp_eq_u32_e64 s[6:7], v65, v4
	v_cmp_eq_u32_e64 s[36:37], v65, v5
	s_waitcnt lgkmcnt(0)
	v_pk_add_f32 v[60:61], v[60:61], v[62:63]
	s_or_b64 s[4:5], s[4:5], s[8:9]
	v_pk_add_f32 v[62:63], v[60:61], s[0:1] op_sel_hi:[1,0]
	s_or_b64 s[6:7], s[6:7], s[36:37]
	v_cndmask_b32_e64 v61, v61, v63, s[4:5]
	v_lshlrev_b32_e32 v63, 6, v64
	v_cndmask_b32_e64 v60, v60, v62, s[6:7]
	v_lshlrev_b32_e32 v62, 6, v65
	v_add_u32_e32 v61, 1, v61
	v_cmp_le_i32_e64 s[4:5], v63, v2
	v_add_u32_e32 v60, 1, v60
	v_or_b32_e32 v70, 12, v15
	v_cndmask_b32_e64 v61, 0, v61, s[4:5]
	v_cmp_le_i32_e64 s[4:5], v62, v2
	v_sub_u32_e32 v62, 0x80, v65
	v_or_b32_e32 v69, 13, v15
	v_cndmask_b32_e64 v63, 0, v60, s[4:5]
	v_sub_u32_e32 v60, 0x80, v64
	v_add_lshl_u32 v64, v68, v70, 2
	v_add_u32_e32 v65, 0, v64
	v_add_u32_e32 v66, s2, v64
	ds_read_b64 v[64:65], v65 offset:36864
	ds_read_b64 v[66:67], v66
	v_cmp_eq_u32_e64 s[4:5], v69, v4
	v_cmp_eq_u32_e64 s[8:9], v69, v5
	v_cmp_eq_u32_e64 s[6:7], v70, v4
	v_cmp_eq_u32_e64 s[36:37], v70, v5
	s_waitcnt lgkmcnt(0)
	v_pk_add_f32 v[64:65], v[64:65], v[66:67]
	s_or_b64 s[4:5], s[4:5], s[8:9]
	v_pk_add_f32 v[66:67], v[64:65], s[0:1] op_sel_hi:[1,0]
	s_or_b64 s[6:7], s[6:7], s[36:37]
	v_cndmask_b32_e64 v65, v65, v67, s[4:5]
	v_lshlrev_b32_e32 v67, 6, v69
	v_sub_u32_e32 v6, 0, v15
	v_cndmask_b32_e64 v64, v64, v66, s[6:7]
	v_lshlrev_b32_e32 v66, 6, v70
	v_add_u32_e32 v65, 1, v65
	v_cmp_le_i32_e64 s[4:5], v67, v2
	v_or_b32_e32 v72, 15, v15
	v_or_b32_e32 v15, 14, v15
	v_add_u32_e32 v64, 1, v64
	v_cndmask_b32_e64 v65, 0, v65, s[4:5]
	v_cmp_le_i32_e64 s[4:5], v66, v2
	v_add_lshl_u32 v68, v68, v15, 2
	v_sub_u32_e32 v66, 0x80, v70
	v_cndmask_b32_e64 v67, 0, v64, s[4:5]
	v_sub_u32_e32 v64, 0x80, v69
	v_add_u32_e32 v69, 0, v68
	v_add_u32_e32 v70, s2, v68
	ds_read_b64 v[68:69], v69 offset:36864
	ds_read_b64 v[70:71], v70
	v_cmp_eq_u32_e64 s[4:5], v72, v4
	v_cmp_eq_u32_e64 s[8:9], v72, v5
	v_cmp_eq_u32_e64 s[6:7], v15, v4
	v_cmp_eq_u32_e64 s[36:37], v15, v5
	s_waitcnt lgkmcnt(0)
	v_pk_add_f32 v[68:69], v[68:69], v[70:71]
	s_or_b64 s[4:5], s[4:5], s[8:9]
	v_pk_add_f32 v[4:5], v[68:69], s[0:1] op_sel_hi:[1,0]
	s_or_b64 s[6:7], s[6:7], s[36:37]
	v_cndmask_b32_e64 v5, v69, v5, s[4:5]
	v_lshlrev_b32_e32 v69, 6, v72
	v_cndmask_b32_e64 v4, v68, v4, s[6:7]
	v_lshlrev_b32_e32 v68, 6, v15
	v_add_u32_e32 v5, 1, v5
	v_cmp_le_i32_e64 s[4:5], v69, v2
	v_sub_u32_e32 v8, 0, v8
	v_add_u32_e32 v4, 1, v4
	v_cndmask_b32_e64 v69, 0, v5, s[4:5]
	v_cmp_le_i32_e64 s[4:5], v68, v2
	v_add_u32_e32 v6, 0x80, v6
	v_add_u32_e32 v8, 0x80, v8
	v_cndmask_b32_e64 v71, 0, v4, s[4:5]
	v_sub_u32_e32 v68, 0x80, v72
	v_sub_u32_e32 v70, 0x80, v15
	v_mov_b32_e32 v4, v1
	v_mov_b32_e32 v15, v1
	v_mov_b32_e32 v2, 0
	s_mov_b32 s2, 16
	v_mov_b32_e32 v5, 0
	s_branch .LBB0_582

; template <class K0Fn, class CFn, class StopFn>
; DI void kv_pipeline(int tid, const bf16* Kb, const bf16* Vb, size_t stride, int ntiles, K0Fn k0fn, CFn compute, StopFn stop, char* smem) {
;   s16x8 k0r, v0r = s16x8{0, 0, 0, 0, 0, 0, 0, 0}, k1r, v1r = s16x8{0, 0, 0, 0, 0, 0, 0, 0};
;   const bool hasV = (Vb != nullptr);
;   if (ntiles > 0) kv_load(tid, Kb, Vb, stride, k0fn(0), k0r, v0r);
;   if (ntiles > 1) kv_load(tid, Kb, Vb, stride, k0fn(1), k1r, v1r);
;   __syncthreads();
;   if (ntiles > 0) kv_store(tid, smem, 0, hasV, k0r, v0r);
;   if (ntiles > 2) kv_load(tid, Kb, Vb, stride, k0fn(2), k0r, v0r);
.LBB0_672:
	s_lshr_b32 s4, s22, 6
	s_lshr_b32 s5, s20, 6
	s_add_u32 s0, s40, 0x1000000
	s_addc_u32 s1, s41, 0
	s_add_u32 s2, s40, 0x1200000
	ds_bpermute_b32 v215, v211, v214
	s_addc_u32 s3, s41, 0
	s_sub_i32 s14, s5, s4
	s_cmp_gt_i32 s14, -1
	s_cselect_b64 s[6:7], -1, 0
	s_and_b32 s8, s22, 0x1fc0
	s_cmp_lt_i32 s14, 0
	s_cbranch_scc1 .LBB0_675
	s_waitcnt vmcnt(1)
	v_add_u32_e32 v2, s8, v14
	v_ashrrev_i32_e32 v3, 31, v2
	v_lshlrev_b64 v[2:3], 7, v[2:3]
	v_lshl_add_u64 v[4:5], s[0:1], 0, v[2:3]
	v_lshl_add_u64 v[4:5], v[4:5], 0, v[0:1]
	v_lshl_add_u64 v[2:3], s[2:3], 0, v[2:3]
	v_lshl_add_u64 v[2:3], v[2:3], 0, v[0:1]
	s_waitcnt vmcnt(0)
	v_mov_b32_e32 v160, v232
	v_mov_b32_e32 v161, v233
	v_mov_b32_e32 v162, v234
	v_mov_b32_e32 v163, v235
	v_mov_b32_e32 v164, v236
	v_mov_b32_e32 v165, v237
	v_mov_b32_e32 v166, v238
	v_mov_b32_e32 v167, v239
	s_cmp_lt_i32 s14, 1
	s_cbranch_scc1 .LBB0_676
.LBB0_674:
	v_add3_u32 v2, s8, 64, v14
	v_ashrrev_i32_e32 v3, 31, v2
	v_lshlrev_b64 v[2:3], 7, v[2:3]
	v_lshl_add_u64 v[4:5], s[0:1], 0, v[2:3]
	v_lshl_add_u64 v[4:5], v[4:5], 0, v[0:1]
	v_lshl_add_u64 v[2:3], s[2:3], 0, v[2:3]
	v_lshl_add_u64 v[2:3], v[2:3], 0, v[0:1]
	s_waitcnt vmcnt(0)
	v_mov_b32_e32 v168, v240
	v_mov_b32_e32 v169, v241
	v_mov_b32_e32 v170, v242
	v_mov_b32_e32 v171, v243
	v_mov_b32_e32 v172, v244
	v_mov_b32_e32 v173, v245
	v_mov_b32_e32 v174, v246
	v_mov_b32_e32 v175, v247
	s_branch .LBB0_677
